# pooling phase: workgroup-to-row-chunk mapping made XCD-contiguous so window halo rows are shared in one XCD's L2
# speedup vs baseline: 1.0030x; 1.0030x over previous
; #define FRESH() int gtid; do { int t_ = threadIdx.x; asm volatile("" : "+v"(t_)); F.tid = t_; F.lane = t_ & 63; gtid = blockIdx.x * (NWAVES * 64) + t_; (void)gtid; } while (0)
; __global__ void __launch_bounds__(NWAVES * 64, 2) mk_fwd(Args args) {
;     ...
;     if (IN(3)) { FRESH();
;         for (int item = gtid; item < (MT / 8) * 256; item += NTHR) {
;             const int cc = item & 255, row0 = (item >> 8) * 8;
;             int base, L; if (row0 < ML) { base = row0 & ~(SEQ - 1); L = SEQ; } else { base = ML + ((row0 - ML) & ~(CTXL - 1)); L = CTXL; }
;             const int t0 = row0 - base, gidx = cc >> 6;
;             const bf16_t* Ub = U + (size_t)base * DM + cc * 8; bf16_t* Pb = P + (size_t)base * DM + cc * 8;
.LBB0_379:
	s_cmp_lt_i32 s86, 4
	s_cselect_b64 s[0:1], -1, 0
	s_add_u32 s6, s84, 0x1a800000
	s_addc_u32 s7, s85, 0
	s_and_b64 s[4:5], s[0:1], s[4:5]
	s_andn2_b64 vcc, exec, s[4:5]
	s_cbranch_vccnz .LBB0_512
	v_mov_b32_e32 v0, v198
	s_mov_b32 s4, 0x90000
	s_and_b32 s8, s2, 7
	s_lshl_b32 s8, s8, 5
	s_lshr_b32 s9, s2, 3
	s_add_i32 s8, s8, s9
	s_cmpk_eq_i32 s63, 0x100
	s_cselect_b32 s8, s8, s2
	v_lshl_add_u32 v130, s8, 9, v0
	v_cmp_gt_i32_e32 vcc, s4, v130
	s_and_saveexec_b64 s[4:5], vcc
	s_cbranch_execz .LBB0_511
	v_mov_b32_e32 v1, 4
	v_lshlrev_b32_sdwa v92, v1, v0 dst_sel:DWORD dst_unused:UNUSED_PAD src0_sel:DWORD src1_sel:BYTE_0
	v_mov_b32_e32 v93, 0
	v_bfe_u32 v131, v0, 6, 2
	v_lshl_add_u64 v[94:95], s[16:17], 0, v[92:93]
	v_lshl_add_u64 v[96:97], s[6:7], 0, v[92:93]
	s_mov_b64 s[8:9], 0
	s_movk_i32 s22, 0x4000
	v_mov_b32_e32 v132, 0x100
	v_mov_b32_e32 v133, 0x800
	v_mov_b32_e32 v134, 0xffffff00
	v_mov_b32_e32 v135, 0xfffff800
	s_mov_b32 s23, 0x8ffff
	s_branch .LBB0_385
